# v038 + packed f32 VALU ops in the attention tile loops (O rescale v_pk_mul, FoX score v_pk_fma) split into scalar pairs (doc 7.5)
# speedup vs baseline: 1.0175x; 1.0175x over previous
; #define LAS __attribute__((address_space(3)))
; #define MFMA32(a, b, c) __builtin_amdgcn_mfma_f32_32x32x16_bf16((a), (b), (c), 0, 0, 0)
;     ...
;             const LAS unsigned char* base = lds + cur * AT_BUF;
;             f32x16 s0, s1;
; #pragma unroll
;             for (int i = 0; i < 16; ++i) { s0[i] = 0.f; s1[i] = 0.f; }
;             {
;                 bf16x8 ka[8];
; #pragma unroll
;                 for (int ks = 0; ks < 8; ++ks) ka[ks] = *(const LAS bf16x8*)(base + koff + ks * 32);
;                 __builtin_amdgcn_sched_barrier(0);
; #pragma unroll
;                 for (int ks = 0; ks < 8; ++ks) s0 = MFMA32(ka[ks], qf[ks], s0);
;                 __builtin_amdgcn_sched_barrier(0);
; #pragma unroll
;                 for (int ks = 0; ks < 8; ++ks) ka[ks] = *(const LAS bf16x8*)(base + 32 * AT_KROW + koff + ks * 32);
;                 __builtin_amdgcn_sched_barrier(0);
; #pragma unroll
;                 for (int ks = 0; ks < 8; ++ks) s1 = MFMA32(ka[ks], qf[ks], s1);
;             }
;             float x[32];
;             const LAS float* cbl = (const LAS float*)(base + AT_KBUF + AT_VBUF);
;             const bool need_mask = (MODE == 0) ? (k0 + 63 > tq0) : true;
;             float mx = NEG;
;             if (MODE == 1) {
; #pragma unroll
;                 for (int i = 0; i < 32; ++i) { const int ii = i & 15, kl = 32 * (i >> 4) + (ii & 7) + 8 * hh + 16 * (ii >> 3); x[i] = t5[(t_row - (k0 + kl)) & 127]; }
.LBB0_563:
	s_and_b32 s29, s25, 1
	s_add_i32 s30, s72, 64
	s_cmp_le_u32 s30, s27
	s_cselect_b64 s[30:31], -1, 0
	s_add_i32 s34, s72, 0x7f
	s_cmp_gt_i32 s34, s28
	s_cselect_b64 s[34:35], -1, 0
	s_and_b64 s[30:31], s[30:31], s[34:35]
	s_andn2_b64 vcc, exec, s[30:31]
	s_cbranch_vccnz .LBB0_565
	s_xor_b32 s30, s29, 1
	s_mul_i32 s30, s30, 0x8d00
	s_add_i32 s30, s30, 0
	v_add_u32_e32 v169, s30, v164
	ds_read_b128 v[64:67], v169
	ds_read_b128 v[80:83], v169 offset:32
	ds_read_b128 v[84:87], v169 offset:64
	ds_read_b128 v[88:91], v169 offset:96
	ds_read_b128 v[92:95], v169 offset:128
	ds_read_b128 v[170:173], v169 offset:160
	ds_read_b128 v[174:177], v169 offset:192
	ds_read_b128 v[178:181], v169 offset:224
	s_waitcnt lgkmcnt(0)
	v_mfma_f32_32x32x16_bf16 v[64:79], v[64:67], v[128:131], 0
	v_mfma_f32_32x32x16_bf16 v[64:79], v[80:83], v[96:99], v[64:79]
	v_mfma_f32_32x32x16_bf16 v[64:79], v[84:87], v[100:103], v[64:79]
	v_mfma_f32_32x32x16_bf16 v[64:79], v[88:91], v[104:107], v[64:79]
	v_mfma_f32_32x32x16_bf16 v[64:79], v[92:95], v[108:111], v[64:79]
	v_mfma_f32_32x32x16_bf16 v[64:79], v[170:173], v[120:123], v[64:79]
	v_mfma_f32_32x32x16_bf16 v[64:79], v[174:177], v[124:127], v[64:79]
	v_mfma_f32_32x32x16_bf16 v[64:79], v[178:181], v[132:135], v[64:79]
	ds_read_b128 v[80:83], v169 offset:8704
	ds_read_b128 v[170:173], v169 offset:8736
	ds_read_b128 v[174:177], v169 offset:8768
	ds_read_b128 v[178:181], v169 offset:8800
	ds_read_b128 v[182:185], v169 offset:8832
	ds_read_b128 v[186:189], v169 offset:8864
	ds_read_b128 v[190:193], v169 offset:8896
	ds_read_b128 v[194:197], v169 offset:8928
	v_add_u32_e32 v169, v145, v167
	v_subrev_u32_e32 v84, 64, v169
	v_and_b32_e32 v84, 0x7f, v84
	v_add_u32_e32 v85, 63, v169
	v_add_u32_e32 v86, 62, v169
	v_add_u32_e32 v87, 61, v169
	v_add_u32_e32 v88, 60, v169
	v_add_u32_e32 v89, 59, v169
	v_add_u32_e32 v90, 58, v169
	v_add_u32_e32 v91, 57, v169
	v_lshl_add_u32 v84, v84, 2, s26
	v_and_b32_e32 v85, 0x7f, v85
	v_and_b32_e32 v86, 0x7f, v86
	v_and_b32_e32 v87, 0x7f, v87
	v_and_b32_e32 v88, 0x7f, v88
	v_and_b32_e32 v89, 0x7f, v89
	v_and_b32_e32 v90, 0x7f, v90
	v_and_b32_e32 v91, 0x7f, v91
	v_lshl_add_u32 v85, v85, 2, s26
	v_lshl_add_u32 v86, v86, 2, s26
	v_lshl_add_u32 v87, v87, 2, s26
	v_lshl_add_u32 v88, v88, 2, s26
	v_lshl_add_u32 v89, v89, 2, s26
	v_lshl_add_u32 v90, v90, 2, s26
	v_lshl_add_u32 v91, v91, 2, s26
	ds_read_b32 v198, v84
	ds_read_b32 v199, v85
	ds_read_b32 v202, v86
	ds_read_b32 v204, v87
	ds_read_b32 v205, v88
	ds_read_b32 v206, v89
	ds_read_b32 v207, v90
	ds_read_b32 v208, v91
	v_add_u32_e32 v84, 48, v169
	v_and_b32_e32 v84, 0x7f, v84
	v_add_u32_e32 v85, 47, v169
	v_add_u32_e32 v86, 46, v169
	v_add_u32_e32 v87, 45, v169
	v_add_u32_e32 v88, 44, v169
	v_add_u32_e32 v89, 43, v169
	v_add_u32_e32 v90, 42, v169
	v_add_u32_e32 v91, 41, v169
	v_lshl_add_u32 v84, v84, 2, s26
	v_and_b32_e32 v85, 0x7f, v85
	v_and_b32_e32 v86, 0x7f, v86
	v_and_b32_e32 v87, 0x7f, v87
	v_and_b32_e32 v88, 0x7f, v88
	v_and_b32_e32 v89, 0x7f, v89
	v_and_b32_e32 v90, 0x7f, v90
	v_and_b32_e32 v91, 0x7f, v91
	v_lshl_add_u32 v85, v85, 2, s26
	v_lshl_add_u32 v86, v86, 2, s26
	v_lshl_add_u32 v87, v87, 2, s26
	v_lshl_add_u32 v88, v88, 2, s26
	v_lshl_add_u32 v89, v89, 2, s26
	v_lshl_add_u32 v90, v90, 2, s26
	v_lshl_add_u32 v91, v91, 2, s26
	ds_read_b32 v209, v84
	ds_read_b32 v210, v85
	ds_read_b32 v211, v86
	ds_read_b32 v212, v87
	ds_read_b32 v213, v88
	ds_read_b32 v214, v89
	ds_read_b32 v215, v90
	ds_read_b32 v216, v91
	v_add_u32_e32 v84, 32, v169
	v_and_b32_e32 v84, 0x7f, v84
	v_lshl_add_u32 v217, v84, 2, s26
	v_add_u32_e32 v84, 31, v169
	v_and_b32_e32 v84, 0x7f, v84
	v_lshl_add_u32 v218, v84, 2, s26
	v_add_u32_e32 v84, 30, v169
	v_and_b32_e32 v84, 0x7f, v84
	v_lshl_add_u32 v219, v84, 2, s26
	s_waitcnt lgkmcnt(0)
	v_mfma_f32_32x32x16_bf16 v[80:95], v[80:83], v[128:131], 0
	v_add_u32_e32 v222, 27, v169
	v_add_u32_e32 v220, 29, v169
	v_add_u32_e32 v221, 28, v169
	v_and_b32_e32 v222, 0x7f, v222
	v_and_b32_e32 v220, 0x7f, v220
	v_and_b32_e32 v221, 0x7f, v221
	v_lshl_add_u32 v220, v220, 2, s26
	v_mfma_f32_32x32x16_bf16 v[80:95], v[170:173], v[96:99], v[80:95]
	v_add_u32_e32 v171, 26, v169
	v_add_u32_e32 v172, 25, v169
	v_and_b32_e32 v171, 0x7f, v171
	v_and_b32_e32 v172, 0x7f, v172
	v_lshl_add_u32 v170, v222, 2, s26
	v_lshl_add_u32 v171, v171, 2, s26
	v_lshl_add_u32 v172, v172, 2, s26
	v_mfma_f32_32x32x16_bf16 v[80:95], v[174:177], v[100:103], v[80:95]
	v_lshl_add_u32 v221, v221, 2, s26
	ds_read_b32 v173, v217
	ds_read_b32 v174, v218
	ds_read_b32 v175, v219
	ds_read_b32 v176, v220
	ds_read_b32 v177, v221
	ds_read_b32 v170, v170
	ds_read_b32 v171, v171
	ds_read_b32 v172, v172
	v_add_u32_e32 v217, 16, v169
	v_and_b32_e32 v217, 0x7f, v217
	v_lshl_add_u32 v217, v217, 2, s26
	v_mfma_f32_32x32x16_bf16 v[80:95], v[178:181], v[104:107], v[80:95]
	v_add_u32_e32 v178, 15, v169
	v_add_u32_e32 v179, 14, v169
	v_add_u32_e32 v180, 13, v169
	v_add_u32_e32 v181, 12, v169
	v_and_b32_e32 v178, 0x7f, v178
	v_and_b32_e32 v179, 0x7f, v179
	v_and_b32_e32 v180, 0x7f, v180
	v_mfma_f32_32x32x16_bf16 v[80:95], v[182:185], v[108:111], v[80:95]
	v_add_u32_e32 v182, 11, v169
	v_add_u32_e32 v183, 10, v169
	v_add_u32_e32 v169, 9, v169
	v_and_b32_e32 v181, 0x7f, v181
	v_and_b32_e32 v182, 0x7f, v182
	v_and_b32_e32 v183, 0x7f, v183
	v_and_b32_e32 v169, 0x7f, v169
	v_mfma_f32_32x32x16_bf16 v[80:95], v[186:189], v[120:123], v[80:95]
	v_lshl_add_u32 v178, v178, 2, s26
	v_lshl_add_u32 v179, v179, 2, s26
	v_lshl_add_u32 v180, v180, 2, s26
	v_lshl_add_u32 v181, v181, 2, s26
	v_lshl_add_u32 v182, v182, 2, s26
	v_lshl_add_u32 v183, v183, 2, s26
	v_lshl_add_u32 v169, v169, 2, s26
;     ...
;             if (MODE == 1) {
; #pragma unroll
;                 for (int i = 0; i < 32; ++i) { const int ii = i & 15, kl = 32 * (i >> 4) + (ii & 7) + 8 * hh + 16 * (ii >> 3); x[i] = t5[(t_row - (k0 + kl)) & 127]; }
;                 __builtin_amdgcn_sched_barrier(0);
;             }
; #pragma unroll
;             for (int i = 0; i < 32; ++i) {
;                 const int blk = i >> 4, ii = i & 15, kl = 32 * blk + (ii & 7) + 8 * hh + 16 * (ii >> 3);
;                 float v = (blk ? s1[ii] : s0[ii]) * SC;
;                 if (MODE == 0) v += cbl[kl];
;                 if (MODE == 1) { const int rel = t_row - (k0 + kl); v = ((unsigned)rel < 128u) ? v + x[i] : NEG; }
;                 x[i] = v;
;             }
;             if (MODE == 0 && need_mask) {
; #pragma unroll
;                 for (int i = 0; i < 32; ++i) { const int ii = i & 15, kl = 32 * (i >> 4) + (ii & 7) + 8 * hh + 16 * (ii >> 3); if (k0 + kl > t_row) x[i] = NEG; }
;             }
; #pragma unroll
;             for (int i = 0; i < 32; ++i) mx = fmaxf(mx, x[i]);
	ds_read_b32 v184, v217
	ds_read_b32 v178, v178
	ds_read_b32 v179, v179
	ds_read_b32 v180, v180
	ds_read_b32 v181, v181
	ds_read_b32 v182, v182
	ds_read_b32 v183, v183
	ds_read_b32 v169, v169
	v_mfma_f32_32x32x16_bf16 v[80:95], v[190:193], v[124:127], v[80:95]
	v_mfma_f32_32x32x16_bf16 v[80:95], v[194:197], v[132:135], v[80:95]
	v_add_u32_e32 v185, v145, v166
	v_subrev_u32_e32 v186, 64, v185
	v_fmac_f32_e32 v198, 0x3e0293ee, v64
	v_cmp_gt_u32_e32 vcc, s33, v186
	v_add_u32_e32 v186, 0xffffffbf, v185
	v_fmac_f32_e32 v199, 0x3e0293ee, v65
	v_cndmask_b32_e32 v64, v242, v198, vcc
	v_cmp_gt_u32_e32 vcc, s33, v186
	v_add_u32_e32 v186, 0xffffffbe, v185
	v_fmac_f32_e32 v202, 0x3e0293ee, v66
	v_cndmask_b32_e32 v65, v242, v199, vcc
	v_cmp_gt_u32_e32 vcc, s33, v186
	v_add_u32_e32 v186, 0xffffffbd, v185
	v_fmac_f32_e32 v204, 0x3e0293ee, v67
	v_cndmask_b32_e32 v66, v242, v202, vcc
	v_cmp_gt_u32_e32 vcc, s33, v186
	v_add_u32_e32 v186, 0xffffffbc, v185
	v_fmac_f32_e32 v205, 0x3e0293ee, v68
	v_cndmask_b32_e32 v67, v242, v204, vcc
	v_cmp_gt_u32_e32 vcc, s33, v186
	v_add_u32_e32 v186, 0xffffffbb, v185
	v_fmac_f32_e32 v206, 0x3e0293ee, v69
	v_cndmask_b32_e32 v68, v242, v205, vcc
	v_cmp_gt_u32_e32 vcc, s33, v186
	v_add_u32_e32 v186, 0xffffffba, v185
	v_fmac_f32_e32 v207, 0x3e0293ee, v70
	v_cndmask_b32_e32 v69, v242, v206, vcc
	v_cmp_gt_u32_e32 vcc, s33, v186
	v_add_u32_e32 v186, 0xffffffb9, v185
	v_fmac_f32_e32 v208, 0x3e0293ee, v71
	v_cndmask_b32_e32 v70, v242, v207, vcc
	v_cmp_gt_u32_e32 vcc, s33, v186
	v_add_u32_e32 v186, 0xffffffb0, v185
	v_fmac_f32_e32 v209, 0x3e0293ee, v72
	v_cndmask_b32_e32 v71, v242, v208, vcc
	v_cmp_gt_u32_e32 vcc, s33, v186
	v_add_u32_e32 v186, 0xffffffaf, v185
	v_fmac_f32_e32 v210, 0x3e0293ee, v73
	v_cndmask_b32_e32 v72, v242, v209, vcc
	v_cmp_gt_u32_e32 vcc, s33, v186
	v_add_u32_e32 v186, 0xffffffae, v185
	v_fmac_f32_e32 v211, 0x3e0293ee, v74
	v_cndmask_b32_e32 v73, v242, v210, vcc
	v_cmp_gt_u32_e32 vcc, s33, v186
	v_add_u32_e32 v186, 0xffffffad, v185
	v_fmac_f32_e32 v212, 0x3e0293ee, v75
	v_cndmask_b32_e32 v74, v242, v211, vcc
	v_cmp_gt_u32_e32 vcc, s33, v186
	v_add_u32_e32 v186, 0xffffffac, v185
	v_fmac_f32_e32 v213, 0x3e0293ee, v76
	v_cndmask_b32_e32 v75, v242, v212, vcc
	v_cmp_gt_u32_e32 vcc, s33, v186
	v_add_u32_e32 v186, 0xffffffab, v185
	v_fmac_f32_e32 v214, 0x3e0293ee, v77
	v_cndmask_b32_e32 v76, v242, v213, vcc
	v_cmp_gt_u32_e32 vcc, s33, v186
	v_add_u32_e32 v186, 0xffffffaa, v185
	v_fmac_f32_e32 v215, 0x3e0293ee, v78
	v_cndmask_b32_e32 v77, v242, v214, vcc
	v_cmp_gt_u32_e32 vcc, s33, v186
	v_add_u32_e32 v186, 0xffffffa9, v185
	v_fmac_f32_e32 v216, 0x3e0293ee, v79
	v_cndmask_b32_e32 v78, v242, v215, vcc
	v_cmp_gt_u32_e32 vcc, s33, v186
	v_add_u32_e32 v186, 0xffffffa0, v185
	s_waitcnt lgkmcnt(0)
	v_fmac_f32_e32 v173, 0x3e0293ee, v80
	v_cndmask_b32_e32 v79, v242, v216, vcc
	v_cmp_gt_u32_e32 vcc, s33, v186
	v_fmac_f32_e32 v174, 0x3e0293ee, v81
	v_fmac_f32_e32 v175, 0x3e0293ee, v82
	v_cndmask_b32_e32 v80, v242, v173, vcc
	v_add_u32_e32 v173, 0xffffff9f, v185
	v_cmp_gt_u32_e32 vcc, s33, v173
	v_add_u32_e32 v173, 0xffffff9e, v185
	v_fmac_f32_e32 v176, 0x3e0293ee, v83
	v_cndmask_b32_e32 v81, v242, v174, vcc
	v_cmp_gt_u32_e32 vcc, s33, v173
	v_add_u32_e32 v173, 0xffffff9d, v185
	v_fmac_f32_e32 v177, 0x3e0293ee, v84
	v_cndmask_b32_e32 v82, v242, v175, vcc
	v_cmp_gt_u32_e32 vcc, s33, v173
	v_add_u32_e32 v173, 0xffffff9c, v185
	v_fmac_f32_e32 v170, 0x3e0293ee, v85
	v_cndmask_b32_e32 v83, v242, v176, vcc
	v_cmp_gt_u32_e32 vcc, s33, v173
	v_add_u32_e32 v173, 0xffffff9b, v185
	v_fmac_f32_e32 v171, 0x3e0293ee, v86
	v_cndmask_b32_e32 v84, v242, v177, vcc
	v_cmp_gt_u32_e32 vcc, s33, v173
	v_fmac_f32_e32 v172, 0x3e0293ee, v87
	v_fmac_f32_e32 v184, 0x3e0293ee, v88
	v_cndmask_b32_e32 v85, v242, v170, vcc
	v_add_u32_e32 v170, 0xffffff9a, v185
	v_cmp_gt_u32_e32 vcc, s33, v170
	v_add_u32_e32 v170, 0xffffff99, v185
	v_fmac_f32_e32 v178, 0x3e0293ee, v89
	v_cndmask_b32_e32 v86, v242, v171, vcc
	v_cmp_gt_u32_e32 vcc, s33, v170
	v_add_u32_e32 v170, 0xffffff90, v185
	v_fmac_f32_e32 v179, 0x3e0293ee, v90
	v_cndmask_b32_e32 v87, v242, v172, vcc
	v_cmp_gt_u32_e32 vcc, s33, v170
	v_add_u32_e32 v170, 0xffffff8f, v185
	v_fmac_f32_e32 v180, 0x3e0293ee, v91
	v_cndmask_b32_e32 v88, v242, v184, vcc
	v_cmp_gt_u32_e32 vcc, s33, v170
	v_add_u32_e32 v170, 0xffffff8e, v185
	v_fmac_f32_e32 v181, 0x3e0293ee, v92
	v_cndmask_b32_e32 v89, v242, v178, vcc
	v_cmp_gt_u32_e32 vcc, s33, v170
	v_add_u32_e32 v170, 0xffffff8d, v185
	v_fmac_f32_e32 v182, 0x3e0293ee, v93
	v_cndmask_b32_e32 v90, v242, v179, vcc
	v_cmp_gt_u32_e32 vcc, s33, v170
	v_add_u32_e32 v170, 0xffffff8c, v185
	v_fmac_f32_e32 v183, 0x3e0293ee, v94
	v_cndmask_b32_e32 v91, v242, v180, vcc
	v_cmp_gt_u32_e32 vcc, s33, v170
	v_add_u32_e32 v170, 0xffffff8b, v185
	v_fmac_f32_e32 v169, 0x3e0293ee, v95
	v_cndmask_b32_e32 v92, v242, v181, vcc
	v_cmp_gt_u32_e32 vcc, s33, v170
	v_add_u32_e32 v170, 0xffffff8a, v185
	s_nop 0
	v_cndmask_b32_e32 v93, v242, v182, vcc
	v_cmp_gt_u32_e32 vcc, s33, v170
	v_add_u32_e32 v170, 0xffffff89, v185
	s_nop 0
	v_cndmask_b32_e32 v94, v242, v183, vcc
	v_cmp_gt_u32_e32 vcc, s33, v170
	s_nop 1
	v_cndmask_b32_e32 v95, v242, v169, vcc
	v_max3_f32 v169, v64, s36, v65
	v_max3_f32 v169, v169, v66, v67
	v_max3_f32 v169, v169, v68, v69
	v_max3_f32 v169, v169, v70, v71
	v_max3_f32 v169, v169, v72, v73
	v_max3_f32 v169, v169, v74, v75
	v_max3_f32 v169, v169, v76, v77
	v_max3_f32 v169, v169, v78, v79
	v_max3_f32 v169, v169, v80, v81
	v_max3_f32 v169, v169, v82, v83
	v_max3_f32 v169, v169, v84, v85
	v_max3_f32 v169, v169, v86, v87
	v_max3_f32 v169, v169, v88, v89
	v_max3_f32 v169, v169, v90, v91
; #define LAS __attribute__((address_space(3)))
; __device__ __forceinline__ float ex2(float x) { return __builtin_amdgcn_exp2f(x); }
; __device__ __forceinline__ float xmax(float v) { const auto r = __builtin_amdgcn_permlane32_swap(__float_as_uint(v), __float_as_uint(v), false, false); return fmaxf(__uint_as_float(r[0]), __uint_as_float(r[1])); }
;     ...
;             for (int i = 0; i < 32; ++i) mx = fmaxf(mx, x[i]);
;             mx = xmax(mx);
;             const float mn = fmaxf(m, mx), alpha = ex2(m - mn); m = mn;
;             float rs = 0.f;
; #pragma unroll
;             for (int i = 0; i < 32; ++i) { x[i] = ex2(x[i] - mn); rs += x[i]; }
;             l = l * alpha + rs;
; #pragma unroll
;             for (int db = 0; db < 4; ++db)
; #pragma unroll
;                 for (int i = 0; i < 16; ++i) o[db][i] *= alpha;
;             bf16x8 pf[4];
; #pragma unroll
;             for (int j = 0; j < 4; ++j) pf[j] = pack8(x[8 * j], x[8 * j + 1], x[8 * j + 2], x[8 * j + 3], x[8 * j + 4], x[8 * j + 5], x[8 * j + 6], x[8 * j + 7]);
; #pragma unroll
;             for (int jh = 0; jh < 2; ++jh) {
;                 bf16x8 va[2][4];
; #pragma unroll
;                 for (int j = 0; j < 2; ++j)
; #pragma unroll
;                     for (int db = 0; db < 4; ++db) va[j][db] = *(const LAS bf16x8*)(base + voff + db * 32 * AT_VROW + (2 * jh + j) * 32);
	v_max3_f32 v169, v169, v92, v93
	v_max3_f32 v169, v169, v94, v95
	v_mov_b32_e32 v170, v169
	s_nop 1
	v_permlane32_swap_b32_e32 v169, v170
	v_max3_f32 v188, v168, v169, v170
	v_sub_f32_e32 v64, v64, v188
	v_exp_f32_e32 v169, v64
	v_sub_f32_e32 v64, v65, v188
	v_exp_f32_e32 v65, v64
	v_sub_f32_e32 v64, v66, v188
	v_exp_f32_e32 v170, v64
	v_sub_f32_e32 v64, v67, v188
	v_sub_f32_e32 v66, v94, v188
	v_exp_f32_e32 v67, v64
	v_sub_f32_e32 v64, v68, v188
	v_exp_f32_e32 v94, v66
	v_sub_f32_e32 v66, v95, v188
	v_exp_f32_e32 v68, v64
	v_sub_f32_e32 v64, v69, v188
	v_exp_f32_e32 v95, v66
	v_add_f32_e32 v66, 0, v169
	v_exp_f32_e32 v69, v64
	v_sub_f32_e32 v64, v70, v188
	v_add_f32_e32 v66, v65, v66
	v_exp_f32_e32 v70, v64
	v_sub_f32_e32 v64, v71, v188
	v_add_f32_e32 v66, v170, v66
	v_exp_f32_e32 v71, v64
	v_sub_f32_e32 v64, v72, v188
	v_add_f32_e32 v66, v67, v66
	v_exp_f32_e32 v72, v64
	v_sub_f32_e32 v64, v73, v188
	v_add_f32_e32 v66, v68, v66
	v_exp_f32_e32 v73, v64
	v_sub_f32_e32 v64, v74, v188
	v_add_f32_e32 v66, v69, v66
	v_exp_f32_e32 v74, v64
	v_sub_f32_e32 v64, v75, v188
	v_add_f32_e32 v66, v70, v66
	v_exp_f32_e32 v75, v64
	v_sub_f32_e32 v64, v76, v188
	v_add_f32_e32 v66, v71, v66
	v_exp_f32_e32 v76, v64
	v_sub_f32_e32 v64, v77, v188
	v_add_f32_e32 v66, v72, v66
	v_exp_f32_e32 v77, v64
	v_sub_f32_e32 v64, v78, v188
	v_add_f32_e32 v66, v73, v66
	v_exp_f32_e32 v78, v64
	v_sub_f32_e32 v64, v79, v188
	v_add_f32_e32 v66, v74, v66
	v_exp_f32_e32 v79, v64
	v_sub_f32_e32 v64, v80, v188
	v_add_f32_e32 v66, v75, v66
	v_exp_f32_e32 v80, v64
	v_sub_f32_e32 v64, v81, v188
	v_add_f32_e32 v66, v76, v66
	v_exp_f32_e32 v81, v64
	v_sub_f32_e32 v64, v82, v188
	v_add_f32_e32 v66, v77, v66
	v_exp_f32_e32 v82, v64
	v_sub_f32_e32 v64, v83, v188
	v_add_f32_e32 v66, v78, v66
	v_exp_f32_e32 v83, v64
	v_sub_f32_e32 v64, v84, v188
	v_add_f32_e32 v66, v79, v66
	v_exp_f32_e32 v84, v64
	v_sub_f32_e32 v64, v85, v188
	v_add_f32_e32 v66, v80, v66
	v_exp_f32_e32 v85, v64
	v_sub_f32_e32 v64, v86, v188
	v_add_f32_e32 v66, v81, v66
	v_exp_f32_e32 v86, v64
	v_sub_f32_e32 v64, v87, v188
	v_add_f32_e32 v66, v82, v66
	v_exp_f32_e32 v87, v64
	v_sub_f32_e32 v64, v88, v188
	v_add_f32_e32 v66, v83, v66
	v_exp_f32_e32 v184, v64
	v_sub_f32_e32 v64, v89, v188
	v_add_f32_e32 v66, v84, v66
	v_exp_f32_e32 v185, v64
	v_sub_f32_e32 v64, v90, v188
	v_add_f32_e32 v66, v85, v66
	v_exp_f32_e32 v186, v64
	v_sub_f32_e32 v64, v91, v188
	v_add_f32_e32 v66, v86, v66
	v_exp_f32_e32 v187, v64
	v_sub_f32_e32 v64, v92, v188
	v_add_f32_e32 v66, v87, v66
	v_exp_f32_e32 v189, v64
	v_sub_f32_e32 v64, v93, v188
	v_add_f32_e32 v66, v184, v66
	v_exp_f32_e32 v190, v64
	v_add_f32_e32 v66, v185, v66
	v_sub_f32_e32 v168, v168, v188
	v_add_f32_e32 v66, v186, v66
	v_exp_f32_e32 v64, v168
	v_add_f32_e32 v66, v187, v66
	v_add_f32_e32 v66, v189, v66
	v_add_f32_e32 v66, v190, v66
	v_add_f32_e32 v66, v94, v66
	v_mul_f32_e32 v62, v62, v64
	v_mul_f32_e32 v63, v63, v64
	v_mul_f32_e32 v60, v60, v64
	v_mul_f32_e32 v61, v61, v64
	v_mul_f32_e32 v58, v58, v64
	v_mul_f32_e32 v59, v59, v64
	v_mul_f32_e32 v56, v56, v64
	v_mul_f32_e32 v57, v57, v64
	v_mul_f32_e32 v54, v54, v64
	v_mul_f32_e32 v55, v55, v64
	v_mul_f32_e32 v52, v52, v64
	v_mul_f32_e32 v53, v53, v64
	v_mul_f32_e32 v50, v50, v64
	v_mul_f32_e32 v51, v51, v64
	v_mul_f32_e32 v48, v48, v64
	v_mul_f32_e32 v49, v49, v64
	v_mul_f32_e32 v46, v46, v64
	v_mul_f32_e32 v47, v47, v64
	v_mul_f32_e32 v44, v44, v64
	v_mul_f32_e32 v45, v45, v64
	v_mul_f32_e32 v42, v42, v64
	v_mul_f32_e32 v43, v43, v64
	v_mul_f32_e32 v40, v40, v64
	v_mul_f32_e32 v41, v41, v64
	v_mul_f32_e32 v38, v38, v64
	v_mul_f32_e32 v39, v39, v64
	v_mul_f32_e32 v36, v36, v64
	v_mul_f32_e32 v37, v37, v64
	v_mul_f32_e32 v34, v34, v64
	v_mul_f32_e32 v35, v35, v64
	v_mul_f32_e32 v32, v32, v64
	v_mul_f32_e32 v33, v33, v64
	v_mul_f32_e32 v30, v30, v64
	v_mul_f32_e32 v31, v31, v64
	v_mul_f32_e32 v28, v28, v64
	v_mul_f32_e32 v29, v29, v64
	v_mul_f32_e32 v26, v26, v64
	v_mul_f32_e32 v27, v27, v64
	v_mul_f32_e32 v24, v24, v64
	v_mul_f32_e32 v25, v25, v64
	v_mul_f32_e32 v22, v22, v64
	v_mul_f32_e32 v23, v23, v64
	v_mul_f32_e32 v20, v20, v64
	v_mul_f32_e32 v21, v21, v64
	v_mul_f32_e32 v18, v18, v64
	v_mul_f32_e32 v19, v19, v64
	v_mul_f32_e32 v16, v16, v64
	v_mul_f32_e32 v17, v17, v64
	v_mul_f32_e32 v14, v14, v64
	v_mul_f32_e32 v15, v15, v64
	v_mul_f32_e32 v12, v12, v64
	v_mul_f32_e32 v13, v13, v64
	v_mul_f32_e32 v10, v10, v64
	v_mul_f32_e32 v11, v11, v64
	v_mul_f32_e32 v8, v8, v64
	v_mul_f32_e32 v9, v9, v64
	v_mul_f32_e32 v6, v6, v64
	v_mul_f32_e32 v7, v7, v64
	v_mul_f32_e32 v4, v4, v64
	v_mul_f32_e32 v5, v5, v64
	v_mul_f32_e32 v2, v2, v64
	v_mul_f32_e32 v3, v3, v64
	v_mul_f32_e32 v0, v0, v64
	v_mul_f32_e32 v1, v1, v64
	v_add_f32_e32 v191, v95, v66
	v_cvt_pk_bf16_f32 v66, v169, v65
	v_add3_u32 v65, s30, v163, v200
	v_cvt_pk_bf16_f32 v67, v170, v67
	v_cvt_pk_bf16_f32 v68, v68, v69
	v_cvt_pk_bf16_f32 v69, v70, v71
	v_cvt_pk_bf16_f32 v70, v72, v73
	v_cvt_pk_bf16_f32 v71, v74, v75
	v_cvt_pk_bf16_f32 v72, v76, v77
	v_cvt_pk_bf16_f32 v73, v78, v79
	v_cvt_pk_bf16_f32 v74, v80, v81
	v_cvt_pk_bf16_f32 v75, v82, v83
	v_cvt_pk_bf16_f32 v76, v84, v85
	v_cvt_pk_bf16_f32 v77, v86, v87
	ds_read_b128 v[78:81], v65 offset:17408
	ds_read_b128 v[82:85], v65 offset:17440
	ds_read_b128 v[86:89], v65 offset:22016
	ds_read_b128 v[90:93], v65 offset:22048
	ds_read_b128 v[168:171], v65 offset:26624
	ds_read_b128 v[172:175], v65 offset:26656
	ds_read_b128 v[176:179], v65 offset:31232
	ds_read_b128 v[180:183], v65 offset:31264
	v_cvt_pk_bf16_f32 v184, v184, v185
	v_cvt_pk_bf16_f32 v185, v186, v187
	v_cvt_pk_bf16_f32 v186, v189, v190
	v_cvt_pk_bf16_f32 v187, v94, v95
	s_waitcnt lgkmcnt(0)
; #define LAS __attribute__((address_space(3)))
; #define MFMA32(a, b, c) __builtin_amdgcn_mfma_f32_32x32x16_bf16((a), (b), (c), 0, 0, 0)
;     ...
;             l = l * alpha + rs;
;     ...
;             for (int jh = 0; jh < 2; ++jh) {
;                 bf16x8 va[2][4];
; #pragma unroll
;                 for (int j = 0; j < 2; ++j)
; #pragma unroll
;                     for (int db = 0; db < 4; ++db) va[j][db] = *(const LAS bf16x8*)(base + voff + db * 32 * AT_VROW + (2 * jh + j) * 32);
;                 __builtin_amdgcn_sched_barrier(0);
; #pragma unroll
;                 for (int j = 0; j < 2; ++j)
; #pragma unroll
;                     for (int db = 0; db < 4; ++db) o[db] = MFMA32(va[j][db], pf[2 * jh + j], o[db]);
;                 __builtin_amdgcn_sched_barrier(0);
;             }
	v_mfma_f32_32x32x16_bf16 v[48:63], v[78:81], v[66:69], v[48:63]
	v_mfma_f32_32x32x16_bf16 v[32:47], v[86:89], v[66:69], v[32:47]
	v_mfma_f32_32x32x16_bf16 v[16:31], v[168:171], v[66:69], v[16:31]
	v_mfma_f32_32x32x16_bf16 v[0:15], v[176:179], v[66:69], v[0:15]
	v_mfma_f32_32x32x16_bf16 v[48:63], v[82:85], v[70:73], v[48:63]
	v_mfma_f32_32x32x16_bf16 v[32:47], v[90:93], v[70:73], v[32:47]
	v_mfma_f32_32x32x16_bf16 v[16:31], v[172:175], v[70:73], v[16:31]
	v_mfma_f32_32x32x16_bf16 v[0:15], v[180:183], v[70:73], v[0:15]
	ds_read_b128 v[66:69], v65 offset:17472
	ds_read_b128 v[70:73], v65 offset:17504
	ds_read_b128 v[78:81], v65 offset:22080
	ds_read_b128 v[82:85], v65 offset:22112
	ds_read_b128 v[86:89], v65 offset:26688
	ds_read_b128 v[90:93], v65 offset:26720
	ds_read_b128 v[168:171], v65 offset:31296
	ds_read_b128 v[172:175], v65 offset:31328
	s_waitcnt lgkmcnt(0)
	v_mfma_f32_32x32x16_bf16 v[48:63], v[66:69], v[74:77], v[48:63]
	v_mfma_f32_32x32x16_bf16 v[32:47], v[78:81], v[74:77], v[32:47]
	v_mfma_f32_32x32x16_bf16 v[16:31], v[86:89], v[74:77], v[16:31]
	v_mfma_f32_32x32x16_bf16 v[0:15], v[168:171], v[74:77], v[0:15]
	v_mfma_f32_32x32x16_bf16 v[48:63], v[70:73], v[184:187], v[48:63]
	v_mfma_f32_32x32x16_bf16 v[32:47], v[82:85], v[184:187], v[32:47]
	v_mfma_f32_32x32x16_bf16 v[16:31], v[90:93], v[184:187], v[16:31]
	v_mfma_f32_32x32x16_bf16 v[0:15], v[172:175], v[184:187], v[0:15]
	v_fmac_f32_e32 v191, v149, v64
	v_mov_b32_e32 v149, v191
	v_mov_b32_e32 v168, v188

; #define LAS __attribute__((address_space(3)))
; #define MFMA32(a, b, c) __builtin_amdgcn_mfma_f32_32x32x16_bf16((a), (b), (c), 0, 0, 0)
;     ...
;             const LAS unsigned char* base = lds + cur * AT_BUF;
;             f32x16 s0, s1;
; #pragma unroll
;             for (int i = 0; i < 16; ++i) { s0[i] = 0.f; s1[i] = 0.f; }
;             {
;                 bf16x8 ka[8];
; #pragma unroll
;                 for (int ks = 0; ks < 8; ++ks) ka[ks] = *(const LAS bf16x8*)(base + koff + ks * 32);
;                 __builtin_amdgcn_sched_barrier(0);
; #pragma unroll
;                 for (int ks = 0; ks < 8; ++ks) s0 = MFMA32(ka[ks], qf[ks], s0);
;                 __builtin_amdgcn_sched_barrier(0);
; #pragma unroll
;                 for (int ks = 0; ks < 8; ++ks) ka[ks] = *(const LAS bf16x8*)(base + 32 * AT_KROW + koff + ks * 32);
;                 __builtin_amdgcn_sched_barrier(0);
; #pragma unroll
;                 for (int ks = 0; ks < 8; ++ks) s1 = MFMA32(ka[ks], qf[ks], s1);
;             }
;             float x[32];
;             const LAS float* cbl = (const LAS float*)(base + AT_KBUF + AT_VBUF);
;             const bool need_mask = (MODE == 0) ? (k0 + 63 > tq0) : true;
;             float mx = NEG;
;             if (MODE == 1) {
; #pragma unroll
;                 for (int i = 0; i < 32; ++i) { const int ii = i & 15, kl = 32 * (i >> 4) + (ii & 7) + 8 * hh + 16 * (ii >> 3); x[i] = t5[(t_row - (k0 + kl)) & 127]; }
;                 __builtin_amdgcn_sched_barrier(0);
;             }
; #pragma unroll
;             for (int i = 0; i < 32; ++i) {
;                 const int blk = i >> 4, ii = i & 15, kl = 32 * blk + (ii & 7) + 8 * hh + 16 * (ii >> 3);
;                 float v = (blk ? s1[ii] : s0[ii]) * SC;
;                 if (MODE == 0) v += cbl[kl];
;                 if (MODE == 1) { const int rel = t_row - (k0 + kl); v = ((unsigned)rel < 128u) ? v + x[i] : NEG; }
;                 x[i] = v;
;             }
;             if (MODE == 0 && need_mask) {
; #pragma unroll
;                 for (int i = 0; i < 32; ++i) { const int ii = i & 15, kl = 32 * (i >> 4) + (ii & 7) + 8 * hh + 16 * (ii >> 3); if (k0 + kl > t_row) x[i] = NEG; }
.LBB0_576:
	s_sub_i32 s14, s18, 63
	s_cmp_gt_i32 s14, s17
	s_cselect_b64 s[20:21], -1, 0
	v_and_b32_e32 v181, 1, v178
	s_or_b64 s[20:21], s[20:21], s[12:13]
	v_xor_b32_e32 v180, 1, v181
	s_and_b64 vcc, exec, s[20:21]
	s_cbranch_vccnz .LBB0_582
	s_mov_b32 s12, 0x8d00
	v_mul_lo_u32 v64, v180, s12
	v_add_u32_e32 v182, 0, v64
	v_add_u32_e32 v166, v182, v173
	ds_read_b128 v[64:67], v166
	ds_read_b128 v[80:83], v166 offset:32
	ds_read_b128 v[84:87], v166 offset:64
	ds_read_b128 v[88:91], v166 offset:96
	ds_read_b128 v[92:95], v166 offset:128
	ds_read_b128 v[158:161], v166 offset:160
	ds_read_b128 v[162:165], v166 offset:192
	ds_read_b128 v[184:187], v166 offset:224
	s_waitcnt lgkmcnt(0)
	v_mfma_f32_32x32x16_bf16 v[64:79], v[64:67], v[96:99], 0
	v_mfma_f32_32x32x16_bf16 v[64:79], v[80:83], v[100:103], v[64:79]
	v_mfma_f32_32x32x16_bf16 v[64:79], v[84:87], v[104:107], v[64:79]
	v_mfma_f32_32x32x16_bf16 v[64:79], v[88:91], v[108:111], v[64:79]
	v_mfma_f32_32x32x16_bf16 v[64:79], v[92:95], v[112:115], v[64:79]
	v_mfma_f32_32x32x16_bf16 v[64:79], v[158:161], v[116:119], v[64:79]
	v_mfma_f32_32x32x16_bf16 v[64:79], v[162:165], v[120:123], v[64:79]
	v_mfma_f32_32x32x16_bf16 v[64:79], v[184:187], v[124:127], v[64:79]
	ds_read_b128 v[80:83], v166 offset:8704
	ds_read_b128 v[158:161], v166 offset:8736
	ds_read_b128 v[162:165], v166 offset:8768
	ds_read_b128 v[184:187], v166 offset:8800
	ds_read_b128 v[188:191], v166 offset:8832
	ds_read_b128 v[192:195], v166 offset:8864
	ds_read_b128 v[196:199], v166 offset:8896
	ds_read_b128 v[204:207], v166 offset:8928
	s_waitcnt lgkmcnt(0)
	v_mfma_f32_32x32x16_bf16 v[80:95], v[80:83], v[96:99], 0
	s_cmp_le_i32 s18, s3
	v_mfma_f32_32x32x16_bf16 v[80:95], v[158:161], v[100:103], v[80:95]
	v_add_u32_e32 v158, v182, v176
	v_mfma_f32_32x32x16_bf16 v[80:95], v[162:165], v[104:107], v[80:95]
	v_mfma_f32_32x32x16_bf16 v[80:95], v[184:187], v[108:111], v[80:95]
	v_mfma_f32_32x32x16_bf16 v[80:95], v[188:191], v[112:115], v[80:95]
	v_mfma_f32_32x32x16_bf16 v[80:95], v[192:195], v[116:119], v[80:95]
	v_mfma_f32_32x32x16_bf16 v[80:95], v[196:199], v[120:123], v[80:95]
	v_mfma_f32_32x32x16_bf16 v[80:95], v[204:207], v[124:127], v[80:95]
	ds_read_b128 v[184:187], v158 offset:35840
	ds_read_b128 v[164:167], v158 offset:35856
	ds_read_b128 v[160:163], v158 offset:35904
	ds_read_b128 v[188:191], v158 offset:35920
	ds_read_b128 v[192:195], v158 offset:35968
	ds_read_b128 v[196:199], v158 offset:35984
	ds_read_b128 v[204:207], v158 offset:36032
	ds_read_b128 v[208:211], v158 offset:36048
	s_waitcnt lgkmcnt(0)
	v_fma_f32 v78, v78, s94, v190
	v_fma_f32 v79, v79, s94, v191
	v_fma_f32 v76, v76, s94, v188
	v_fma_f32 v77, v77, s94, v189
	v_fma_f32 v158, v74, s94, v162
	v_fma_f32 v159, v75, s94, v163
	v_fma_f32 v160, v72, s94, v160
	v_fma_f32 v161, v73, s94, v161
	v_fma_f32 v162, v70, s94, v166
	v_fma_f32 v163, v71, s94, v167
	v_fma_f32 v164, v68, s94, v164
	v_fma_f32 v165, v69, s94, v165
	v_fma_f32 v166, v66, s94, v186
	v_fma_f32 v167, v67, s94, v187
	v_fma_f32 v66, v94, s94, v210
	v_fma_f32 v67, v95, s94, v211
	v_fma_f32 v68, v92, s94, v208
	v_fma_f32 v69, v93, s94, v209
	v_fma_f32 v70, v90, s94, v206
	v_fma_f32 v71, v91, s94, v207
	v_fma_f32 v72, v88, s94, v204
	v_fma_f32 v73, v89, s94, v205
	v_fma_f32 v74, v86, s94, v198
	v_fma_f32 v75, v87, s94, v199
	v_fma_f32 v84, v84, s94, v196
	v_fma_f32 v85, v85, s94, v197
	v_fma_f32 v82, v82, s94, v194
	v_fma_f32 v83, v83, s94, v195
	v_fma_f32 v86, v64, s94, v184
	v_fma_f32 v87, v65, s94, v185
	v_fma_f32 v80, v80, s94, v192
	v_fma_f32 v81, v81, s94, v193
	s_cbranch_scc1 .LBB0_579
	v_add_u32_e32 v64, s18, v151
	v_subrev_u32_e32 v65, 63, v64
	v_cmp_lt_i32_e32 vcc, v65, v146
	s_nop 1
	v_cndmask_b32_e32 v87, v242, v87, vcc
	v_cmp_le_i32_e32 vcc, v65, v146
	v_subrev_u32_e32 v65, 61, v64
	s_nop 0
	v_cndmask_b32_e32 v86, v242, v86, vcc
	v_cmp_le_i32_e32 vcc, v65, v146
	v_subrev_u32_e32 v65, 60, v64
	s_nop 0
	v_cndmask_b32_e32 v166, v242, v166, vcc
	v_cmp_le_i32_e32 vcc, v65, v146
	v_subrev_u32_e32 v65, 59, v64
	s_nop 0
	v_cndmask_b32_e32 v167, v242, v167, vcc
	v_cmp_le_i32_e32 vcc, v65, v146
	v_subrev_u32_e32 v65, 58, v64
	s_nop 0
	v_cndmask_b32_e32 v164, v242, v164, vcc
	v_cmp_le_i32_e32 vcc, v65, v146
	v_subrev_u32_e32 v65, 57, v64
	s_nop 0
	v_cndmask_b32_e32 v165, v242, v165, vcc
	v_cmp_le_i32_e32 vcc, v65, v146
	v_subrev_u32_e32 v65, 56, v64
	s_nop 0
	v_cndmask_b32_e32 v162, v242, v162, vcc
	v_cmp_le_i32_e32 vcc, v65, v146
	v_subrev_u32_e32 v65, 47, v64
	s_nop 0
	v_cndmask_b32_e32 v163, v242, v163, vcc
	v_cmp_le_i32_e32 vcc, v65, v146
	v_subrev_u32_e32 v65, 46, v64
	s_nop 0
	v_cndmask_b32_e32 v160, v242, v160, vcc
	v_cmp_le_i32_e32 vcc, v65, v146
	v_subrev_u32_e32 v65, 45, v64
	s_nop 0
	v_cndmask_b32_e32 v161, v242, v161, vcc
	v_cmp_le_i32_e32 vcc, v65, v146
	v_subrev_u32_e32 v65, 44, v64
	s_nop 0
	v_cndmask_b32_e32 v158, v242, v158, vcc
	v_cmp_le_i32_e32 vcc, v65, v146
	v_subrev_u32_e32 v65, 43, v64
	s_nop 0
	v_cndmask_b32_e32 v159, v242, v159, vcc
	v_cmp_le_i32_e32 vcc, v65, v146
	v_subrev_u32_e32 v65, 42, v64
	s_nop 0
	v_cndmask_b32_e32 v76, v242, v76, vcc
	v_cmp_le_i32_e32 vcc, v65, v146
	v_subrev_u32_e32 v65, 41, v64
	s_nop 0
	v_cndmask_b32_e32 v77, v242, v77, vcc
	v_cmp_le_i32_e32 vcc, v65, v146
	v_subrev_u32_e32 v65, 40, v64
	s_nop 0
	v_cndmask_b32_e32 v78, v242, v78, vcc
	v_cmp_le_i32_e32 vcc, v65, v146
	v_subrev_u32_e32 v65, 31, v64
	s_nop 0
	v_cndmask_b32_e32 v79, v242, v79, vcc
	v_cmp_le_i32_e32 vcc, v65, v146
	v_subrev_u32_e32 v65, 30, v64
	s_nop 0
	v_cndmask_b32_e32 v80, v242, v80, vcc
	v_cmp_le_i32_e32 vcc, v65, v146
	v_subrev_u32_e32 v65, 29, v64
	s_nop 0
	v_cndmask_b32_e32 v81, v242, v81, vcc
;     ...
;             if (MODE == 0 && need_mask) {
; #pragma unroll
;                 for (int i = 0; i < 32; ++i) { const int ii = i & 15, kl = 32 * (i >> 4) + (ii & 7) + 8 * hh + 16 * (ii >> 3); if (k0 + kl > t_row) x[i] = NEG; }
;             }
	v_cmp_le_i32_e32 vcc, v65, v146
	v_subrev_u32_e32 v65, 28, v64
	s_nop 0
	v_cndmask_b32_e32 v82, v242, v82, vcc
	v_cmp_le_i32_e32 vcc, v65, v146
	v_subrev_u32_e32 v65, 27, v64
	s_nop 0
	v_cndmask_b32_e32 v83, v242, v83, vcc
	v_cmp_le_i32_e32 vcc, v65, v146
	v_subrev_u32_e32 v65, 26, v64
	s_nop 0
	v_cndmask_b32_e32 v84, v242, v84, vcc
	v_cmp_le_i32_e32 vcc, v65, v146
	v_subrev_u32_e32 v65, 25, v64
	s_nop 0
	v_cndmask_b32_e32 v85, v242, v85, vcc
	v_cmp_le_i32_e32 vcc, v65, v146
	v_subrev_u32_e32 v65, 24, v64
	s_nop 0
	v_cndmask_b32_e32 v74, v242, v74, vcc
	v_cmp_le_i32_e32 vcc, v65, v146
	v_add_u32_e32 v65, -15, v64
	s_nop 0
	v_cndmask_b32_e32 v75, v242, v75, vcc
	v_cmp_le_i32_e32 vcc, v65, v146
	v_add_u32_e32 v65, -14, v64
	s_nop 0
	v_cndmask_b32_e32 v72, v242, v72, vcc
	v_cmp_le_i32_e32 vcc, v65, v146
	v_add_u32_e32 v65, -13, v64
	s_nop 0
	v_cndmask_b32_e32 v73, v242, v73, vcc
	v_cmp_le_i32_e32 vcc, v65, v146
	v_add_u32_e32 v65, -12, v64
	s_nop 0
	v_cndmask_b32_e32 v70, v242, v70, vcc
	v_cmp_le_i32_e32 vcc, v65, v146
	v_add_u32_e32 v65, -11, v64
	s_nop 0
	v_cndmask_b32_e32 v71, v242, v71, vcc
	v_cmp_le_i32_e32 vcc, v65, v146
	v_add_u32_e32 v65, -10, v64
	s_nop 0
	v_cndmask_b32_e32 v68, v242, v68, vcc
	v_cmp_le_i32_e32 vcc, v65, v146
	v_add_u32_e32 v65, -9, v64
	v_add_u32_e32 v64, -8, v64
	v_cndmask_b32_e32 v69, v242, v69, vcc
	v_cmp_le_i32_e32 vcc, v65, v146
	s_nop 1
	v_cndmask_b32_e32 v66, v242, v66, vcc
	v_cmp_le_i32_e32 vcc, v64, v146
	s_nop 1
	v_cndmask_b32_e32 v67, v242, v67, vcc
; #define LAS __attribute__((address_space(3)))
; __device__ __forceinline__ float ex2(float x) { return __builtin_amdgcn_exp2f(x); }
; __device__ __forceinline__ float xmax(float v) { const auto r = __builtin_amdgcn_permlane32_swap(__float_as_uint(v), __float_as_uint(v), false, false); return fmaxf(__uint_as_float(r[0]), __uint_as_float(r[1])); }
; #define MFMA32(a, b, c) __builtin_amdgcn_mfma_f32_32x32x16_bf16((a), (b), (c), 0, 0, 0)
;     ...
;             for (int i = 0; i < 32; ++i) mx = fmaxf(mx, x[i]);
;             mx = xmax(mx);
;             const float mn = fmaxf(m, mx), alpha = ex2(m - mn); m = mn;
;             float rs = 0.f;
; #pragma unroll
;             for (int i = 0; i < 32; ++i) { x[i] = ex2(x[i] - mn); rs += x[i]; }
;             l = l * alpha + rs;
; #pragma unroll
;             for (int db = 0; db < 4; ++db)
; #pragma unroll
;                 for (int i = 0; i < 16; ++i) o[db][i] *= alpha;
;             bf16x8 pf[4];
; #pragma unroll
;             for (int j = 0; j < 4; ++j) pf[j] = pack8(x[8 * j], x[8 * j + 1], x[8 * j + 2], x[8 * j + 3], x[8 * j + 4], x[8 * j + 5], x[8 * j + 6], x[8 * j + 7]);
; #pragma unroll
;             for (int jh = 0; jh < 2; ++jh) {
;                 bf16x8 va[2][4];
; #pragma unroll
;                 for (int j = 0; j < 2; ++j)
; #pragma unroll
;                     for (int db = 0; db < 4; ++db) va[j][db] = *(const LAS bf16x8*)(base + voff + db * 32 * AT_VROW + (2 * jh + j) * 32);
;                 __builtin_amdgcn_sched_barrier(0);
; #pragma unroll
;                 for (int j = 0; j < 2; ++j)
; #pragma unroll
;                     for (int db = 0; db < 4; ++db) o[db] = MFMA32(va[j][db], pf[2 * jh + j], o[db]);
;                 __builtin_amdgcn_sched_barrier(0);
;             }
;             if (MODE == 0 && kt > kt0 && k0 <= tq0) {
;                 const float ub = qn + cbl[0];
;                 wdone = __all(ub < m - 30.f);
.LBB0_579:
	v_max3_f32 v64, v86, s36, v87
	v_max3_f32 v64, v64, v166, v167
	v_max3_f32 v64, v64, v164, v165
	v_max3_f32 v64, v64, v162, v163
	v_max3_f32 v64, v64, v160, v161
	v_max3_f32 v64, v64, v158, v159
	v_max3_f32 v64, v64, v76, v77
	v_max3_f32 v64, v64, v78, v79
	v_max3_f32 v64, v64, v80, v81
	v_max3_f32 v64, v64, v82, v83
	v_max3_f32 v64, v64, v84, v85
	v_max3_f32 v64, v64, v74, v75
	v_max3_f32 v64, v64, v72, v73
	v_max3_f32 v64, v64, v70, v71
	v_max3_f32 v64, v64, v68, v69
	v_max3_f32 v64, v64, v66, v67
	v_mov_b32_e32 v65, v64
	s_nop 1
	v_permlane32_swap_b32_e32 v64, v65
	v_max3_f32 v65, v183, v64, v65
	v_sub_f32_e32 v64, v183, v65
	v_sub_f32_e32 v94, v160, v65
	v_sub_f32_e32 v160, v66, v65
	v_exp_f32_e32 v66, v64
	v_sub_f32_e32 v64, v67, v65
	v_exp_f32_e32 v67, v64
	v_add3_u32 v64, v182, v174, v200
	ds_read_b128 v[192:195], v64 offset:17408
	ds_read_b128 v[196:199], v64 offset:17440
	ds_read_b128 v[204:207], v64 offset:22016
	ds_read_b128 v[208:211], v64 offset:22048
	ds_read_b128 v[212:215], v64 offset:26624
	ds_read_b128 v[216:219], v64 offset:26656
	ds_read_b128 v[220:223], v64 offset:31232
	ds_read_b128 v[224:227], v64 offset:31264
	v_sub_f32_e32 v86, v86, v65
	v_sub_f32_e32 v87, v87, v65
	v_sub_f32_e32 v88, v166, v65
	v_sub_f32_e32 v89, v167, v65
	v_sub_f32_e32 v90, v164, v65
	v_sub_f32_e32 v91, v165, v65
	v_sub_f32_e32 v92, v162, v65
	v_sub_f32_e32 v93, v163, v65
	v_sub_f32_e32 v95, v161, v65
	v_sub_f32_e32 v158, v158, v65
	v_sub_f32_e32 v159, v159, v65
	v_sub_f32_e32 v76, v76, v65
	v_sub_f32_e32 v77, v77, v65
	v_sub_f32_e32 v78, v78, v65
	v_sub_f32_e32 v79, v79, v65
	v_sub_f32_e32 v80, v80, v65
	v_sub_f32_e32 v81, v81, v65
	v_sub_f32_e32 v82, v82, v65
	v_sub_f32_e32 v83, v83, v65
	v_sub_f32_e32 v84, v84, v65
	v_sub_f32_e32 v85, v85, v65
	v_sub_f32_e32 v74, v74, v65
	v_sub_f32_e32 v75, v75, v65
	v_sub_f32_e32 v72, v72, v65
	v_sub_f32_e32 v73, v73, v65
	v_sub_f32_e32 v70, v70, v65
	v_sub_f32_e32 v71, v71, v65
	v_sub_f32_e32 v68, v68, v65
	v_sub_f32_e32 v69, v69, v65
	v_exp_f32_e32 v86, v86
	v_exp_f32_e32 v87, v87
	v_exp_f32_e32 v88, v88
	v_exp_f32_e32 v89, v89
	v_exp_f32_e32 v90, v90
	v_exp_f32_e32 v91, v91
	v_exp_f32_e32 v92, v92
	v_exp_f32_e32 v93, v93
	v_exp_f32_e32 v94, v94
	v_exp_f32_e32 v95, v95
	v_exp_f32_e32 v158, v158
	v_exp_f32_e32 v159, v159
	v_exp_f32_e32 v76, v76
	v_exp_f32_e32 v77, v77
	v_exp_f32_e32 v78, v78
	v_exp_f32_e32 v79, v79
	v_exp_f32_e32 v80, v80
	v_exp_f32_e32 v81, v81
	v_exp_f32_e32 v82, v82
	v_exp_f32_e32 v83, v83
	v_exp_f32_e32 v84, v84
	v_exp_f32_e32 v85, v85
	v_exp_f32_e32 v74, v74
	v_exp_f32_e32 v75, v75
	v_exp_f32_e32 v72, v72
	v_exp_f32_e32 v73, v73
	v_exp_f32_e32 v70, v70
	v_exp_f32_e32 v71, v71
	v_exp_f32_e32 v68, v68
	v_exp_f32_e32 v69, v69
	v_exp_f32_e32 v160, v160
	v_mul_f32_e32 v62, v62, v66
	v_mul_f32_e32 v63, v63, v66
	v_mul_f32_e32 v60, v60, v66
	v_mul_f32_e32 v61, v61, v66
	v_mul_f32_e32 v58, v58, v66
	v_mul_f32_e32 v59, v59, v66
	v_mul_f32_e32 v56, v56, v66
	v_mul_f32_e32 v57, v57, v66
	v_mul_f32_e32 v54, v54, v66
	v_mul_f32_e32 v55, v55, v66
	v_mul_f32_e32 v52, v52, v66
	v_mul_f32_e32 v53, v53, v66
	v_mul_f32_e32 v50, v50, v66
	v_mul_f32_e32 v51, v51, v66
	v_mul_f32_e32 v48, v48, v66
	v_mul_f32_e32 v49, v49, v66
	v_mul_f32_e32 v46, v46, v66
	v_mul_f32_e32 v47, v47, v66
	v_mul_f32_e32 v44, v44, v66
	v_mul_f32_e32 v45, v45, v66
	v_mul_f32_e32 v42, v42, v66
	v_mul_f32_e32 v43, v43, v66
	v_mul_f32_e32 v40, v40, v66
	v_mul_f32_e32 v41, v41, v66
	v_mul_f32_e32 v38, v38, v66
	v_mul_f32_e32 v39, v39, v66
	v_mul_f32_e32 v36, v36, v66
	v_mul_f32_e32 v37, v37, v66
	v_mul_f32_e32 v34, v34, v66
	v_mul_f32_e32 v35, v35, v66
	v_mul_f32_e32 v32, v32, v66
	v_mul_f32_e32 v33, v33, v66
	v_mul_f32_e32 v30, v30, v66
	v_mul_f32_e32 v31, v31, v66
	v_mul_f32_e32 v28, v28, v66
	v_mul_f32_e32 v29, v29, v66
	v_mul_f32_e32 v26, v26, v66
	v_mul_f32_e32 v27, v27, v66
	v_mul_f32_e32 v24, v24, v66
	v_mul_f32_e32 v25, v25, v66
	v_mul_f32_e32 v22, v22, v66
	v_mul_f32_e32 v23, v23, v66
	v_mul_f32_e32 v20, v20, v66
	v_mul_f32_e32 v21, v21, v66
	v_mul_f32_e32 v18, v18, v66
	v_mul_f32_e32 v19, v19, v66
	v_mul_f32_e32 v16, v16, v66
	v_mul_f32_e32 v17, v17, v66
	v_mul_f32_e32 v14, v14, v66
	v_mul_f32_e32 v15, v15, v66
	v_mul_f32_e32 v12, v12, v66
	v_mul_f32_e32 v13, v13, v66
	v_mul_f32_e32 v10, v10, v66
	v_mul_f32_e32 v11, v11, v66
	v_mul_f32_e32 v8, v8, v66
	v_mul_f32_e32 v9, v9, v66
	v_mul_f32_e32 v6, v6, v66
	v_mul_f32_e32 v7, v7, v66
	v_mul_f32_e32 v4, v4, v66
	v_mul_f32_e32 v5, v5, v66
	v_mul_f32_e32 v2, v2, v66
	v_mul_f32_e32 v3, v3, v66
	v_mul_f32_e32 v0, v0, v66
	v_mul_f32_e32 v1, v1, v66
	v_cvt_pk_bf16_f32 v162, v86, v87
	v_cvt_pk_bf16_f32 v163, v88, v89
	v_cvt_pk_bf16_f32 v164, v90, v91
	v_cvt_pk_bf16_f32 v165, v92, v93
	v_cvt_pk_bf16_f32 v184, v94, v95
	v_cvt_pk_bf16_f32 v185, v158, v159
	v_cvt_pk_bf16_f32 v186, v76, v77
	v_cvt_pk_bf16_f32 v187, v78, v79
	v_cvt_pk_bf16_f32 v188, v80, v81
	v_cvt_pk_bf16_f32 v189, v82, v83
	v_cvt_pk_bf16_f32 v190, v84, v85
	v_cvt_pk_bf16_f32 v191, v74, v75
	v_cvt_pk_bf16_f32 v228, v72, v73
	v_cvt_pk_bf16_f32 v229, v70, v71
	v_cvt_pk_bf16_f32 v230, v68, v69
	v_cvt_pk_bf16_f32 v231, v160, v67
	s_waitcnt lgkmcnt(0)
	v_mfma_f32_32x32x16_bf16 v[48:63], v[192:195], v[162:165], v[48:63]
	v_mfma_f32_32x32x16_bf16 v[32:47], v[204:207], v[162:165], v[32:47]
	v_mfma_f32_32x32x16_bf16 v[16:31], v[212:215], v[162:165], v[16:31]
	v_mfma_f32_32x32x16_bf16 v[0:15], v[220:223], v[162:165], v[0:15]
	v_mfma_f32_32x32x16_bf16 v[48:63], v[196:199], v[184:187], v[48:63]
	v_mfma_f32_32x32x16_bf16 v[32:47], v[208:211], v[184:187], v[32:47]
	v_mfma_f32_32x32x16_bf16 v[16:31], v[216:219], v[184:187], v[16:31]
	v_mfma_f32_32x32x16_bf16 v[0:15], v[224:227], v[184:187], v[0:15]
	ds_read_b128 v[162:165], v64 offset:17472
	ds_read_b128 v[184:187], v64 offset:17504
	ds_read_b128 v[192:195], v64 offset:22080
	ds_read_b128 v[196:199], v64 offset:22112
	ds_read_b128 v[204:207], v64 offset:26688
	ds_read_b128 v[208:211], v64 offset:26720
	ds_read_b128 v[212:215], v64 offset:31296
	ds_read_b128 v[216:219], v64 offset:31328
	s_waitcnt lgkmcnt(0)
	v_mfma_f32_32x32x16_bf16 v[48:63], v[162:165], v[188:191], v[48:63]
	v_mfma_f32_32x32x16_bf16 v[32:47], v[192:195], v[188:191], v[32:47]
	v_mfma_f32_32x32x16_bf16 v[16:31], v[204:207], v[188:191], v[16:31]
	v_mfma_f32_32x32x16_bf16 v[0:15], v[212:215], v[188:191], v[0:15]
	v_mfma_f32_32x32x16_bf16 v[48:63], v[184:187], v[228:231], v[48:63]
	v_mfma_f32_32x32x16_bf16 v[32:47], v[196:199], v[228:231], v[32:47]
	v_mfma_f32_32x32x16_bf16 v[16:31], v[208:211], v[228:231], v[16:31]
	v_mfma_f32_32x32x16_bf16 v[0:15], v[216:219], v[228:231], v[0:15]
	s_cmp_gt_i32 s14, s3
	s_cselect_b64 s[12:13], -1, 0
	s_or_b64 s[14:15], s[4:5], s[12:13]
	s_mov_b64 s[12:13], 0
	s_and_b64 vcc, exec, s[14:15]
	s_cbranch_vccnz .LBB0_581
	ds_read_b32 v64, v182 offset:35840
	s_waitcnt lgkmcnt(0)
	v_pk_add_f32 v[162:163], v[202:203], v[64:65]
	s_nop 0
	v_cmp_lt_f32_e32 vcc, v162, v163
	s_cmp_eq_u64 vcc, exec
	s_cselect_b64 s[12:13], -1, 0

; #define LAS __attribute__((address_space(3)))
;     ...
;             const LAS unsigned char* base = lds + cur * AT_BUF;
;             f32x16 s0, s1;
; #pragma unroll
;             for (int i = 0; i < 16; ++i) { s0[i] = 0.f; s1[i] = 0.f; }
;             {
;                 bf16x8 ka[8];
; #pragma unroll
;                 for (int ks = 0; ks < 8; ++ks) ka[ks] = *(const LAS bf16x8*)(base + koff + ks * 32);
;                 __builtin_amdgcn_sched_barrier(0);
; #pragma unroll
;                 for (int ks = 0; ks < 8; ++ks) s0 = MFMA32(ka[ks], qf[ks], s0);
;                 __builtin_amdgcn_sched_barrier(0);
; #pragma unroll
;                 for (int ks = 0; ks < 8; ++ks) ka[ks] = *(const LAS bf16x8*)(base + 32 * AT_KROW + koff + ks * 32);
;                 __builtin_amdgcn_sched_barrier(0);
; #pragma unroll
;                 for (int ks = 0; ks < 8; ++ks) s1 = MFMA32(ka[ks], qf[ks], s1);
;             }
;             float x[32];
;             const LAS float* cbl = (const LAS float*)(base + AT_KBUF + AT_VBUF);
;             const bool need_mask = (MODE == 0) ? (k0 + 63 > tq0) : true;
;             float mx = NEG;
;             if (MODE == 1) {
; #pragma unroll
;                 for (int i = 0; i < 32; ++i) { const int ii = i & 15, kl = 32 * (i >> 4) + (ii & 7) + 8 * hh + 16 * (ii >> 3); x[i] = t5[(t_row - (k0 + kl)) & 127]; }
;                 __builtin_amdgcn_sched_barrier(0);
;             }
; #pragma unroll
;             for (int i = 0; i < 32; ++i) {
;                 const int blk = i >> 4, ii = i & 15, kl = 32 * blk + (ii & 7) + 8 * hh + 16 * (ii >> 3);
;                 float v = (blk ? s1[ii] : s0[ii]) * SC;
;                 if (MODE == 0) v += cbl[kl];
;                 if (MODE == 1) { const int rel = t_row - (k0 + kl); v = ((unsigned)rel < 128u) ? v + x[i] : NEG; }
;                 x[i] = v;
;             }
;             if (MODE == 0 && need_mask) {
; #pragma unroll
;                 for (int i = 0; i < 32; ++i) { const int ii = i & 15, kl = 32 * (i >> 4) + (ii & 7) + 8 * hh + 16 * (ii >> 3); if (k0 + kl > t_row) x[i] = NEG; }
;             }
; #pragma unroll
;             for (int i = 0; i < 32; ++i) mx = fmaxf(mx, x[i]);
;             mx = xmax(mx);
;             const float mn = fmaxf(m, mx), alpha = ex2(m - mn); m = mn;
;             float rs = 0.f;
; #pragma unroll
;             for (int i = 0; i < 32; ++i) { x[i] = ex2(x[i] - mn); rs += x[i]; }
.LBB0_774:
	s_and_b32 s8, s13, 1
	s_xor_b32 s9, s8, 1
	s_mul_i32 s9, s9, 0x8d00
	s_add_i32 s9, s9, 0
	v_add_u32_e32 v162, s9, v158
	ds_read_b128 v[64:67], v162
	ds_read_b128 v[68:71], v162 offset:32
	ds_read_b128 v[72:75], v162 offset:64
	ds_read_b128 v[76:79], v162 offset:96
	ds_read_b128 v[164:167], v162 offset:128
	ds_read_b128 v[168:171], v162 offset:160
	ds_read_b128 v[172:175], v162 offset:192
	ds_read_b128 v[176:179], v162 offset:224
	s_waitcnt lgkmcnt(0)
	v_mfma_f32_32x32x16_bf16 v[80:95], v[64:67], v[96:99], 0
	v_mfma_f32_32x32x16_bf16 v[80:95], v[68:71], v[100:103], v[80:95]
	v_mfma_f32_32x32x16_bf16 v[80:95], v[72:75], v[104:107], v[80:95]
	v_mfma_f32_32x32x16_bf16 v[80:95], v[76:79], v[108:111], v[80:95]
	v_mfma_f32_32x32x16_bf16 v[80:95], v[164:167], v[112:115], v[80:95]
	v_mfma_f32_32x32x16_bf16 v[80:95], v[168:171], v[116:119], v[80:95]
	v_mfma_f32_32x32x16_bf16 v[80:95], v[172:175], v[120:123], v[80:95]
	v_mfma_f32_32x32x16_bf16 v[80:95], v[176:179], v[124:127], v[80:95]
	ds_read_b128 v[64:67], v162 offset:8704
	ds_read_b128 v[164:167], v162 offset:8736
	ds_read_b128 v[168:171], v162 offset:8768
	ds_read_b128 v[172:175], v162 offset:8800
	ds_read_b128 v[176:179], v162 offset:8832
	ds_read_b128 v[180:183], v162 offset:8864
	ds_read_b128 v[184:187], v162 offset:8896
	ds_read_b128 v[188:191], v162 offset:8928
	s_waitcnt lgkmcnt(0)
	v_mfma_f32_32x32x16_bf16 v[64:79], v[64:67], v[96:99], 0
	s_nop 1
	v_mul_f32_e32 v162, 0x3e0293ee, v80
	v_add3_u32 v202, s9, v159, v200
	v_mfma_f32_32x32x16_bf16 v[64:79], v[164:167], v[100:103], v[64:79]
	v_mul_f32_e32 v164, 0x3e0293ee, v81
	v_mul_f32_e32 v165, 0x3e0293ee, v82
	v_mul_f32_e32 v166, 0x3e0293ee, v83
	v_max3_f32 v162, v162, s36, v164
	v_mul_f32_e32 v167, 0x3e0293ee, v84
	v_max3_f32 v162, v162, v165, v166
	v_mfma_f32_32x32x16_bf16 v[64:79], v[168:171], v[104:107], v[64:79]
	v_mul_f32_e32 v168, 0x3e0293ee, v85
	v_mul_f32_e32 v169, 0x3e0293ee, v86
	v_mul_f32_e32 v170, 0x3e0293ee, v87
	v_max3_f32 v162, v162, v167, v168
	v_mul_f32_e32 v171, 0x3e0293ee, v88
	v_max3_f32 v162, v162, v169, v170
	v_mfma_f32_32x32x16_bf16 v[64:79], v[172:175], v[108:111], v[64:79]
	v_mul_f32_e32 v172, 0x3e0293ee, v89
	v_mul_f32_e32 v173, 0x3e0293ee, v90
	v_mul_f32_e32 v174, 0x3e0293ee, v91
	v_max3_f32 v162, v162, v171, v172
	v_mul_f32_e32 v175, 0x3e0293ee, v92
	v_max3_f32 v162, v162, v173, v174
	v_mfma_f32_32x32x16_bf16 v[64:79], v[176:179], v[112:115], v[64:79]
	v_mul_f32_e32 v176, 0x3e0293ee, v93
	v_mul_f32_e32 v177, 0x3e0293ee, v94
	v_mul_f32_e32 v178, 0x3e0293ee, v95
	v_max3_f32 v162, v162, v175, v176
	v_max3_f32 v162, v162, v177, v178
	v_mfma_f32_32x32x16_bf16 v[64:79], v[180:183], v[116:119], v[64:79]
	v_mfma_f32_32x32x16_bf16 v[64:79], v[184:187], v[120:123], v[64:79]
	v_mfma_f32_32x32x16_bf16 v[64:79], v[188:191], v[124:127], v[64:79]
	s_nop 11
	v_mul_f32_e32 v164, 0x3e0293ee, v64
	v_mul_f32_e32 v165, 0x3e0293ee, v65
	v_mul_f32_e32 v166, 0x3e0293ee, v66
	v_mul_f32_e32 v167, 0x3e0293ee, v67
	v_max3_f32 v162, v162, v164, v165
	v_mul_f32_e32 v168, 0x3e0293ee, v68
	v_mul_f32_e32 v169, 0x3e0293ee, v69
	v_max3_f32 v162, v162, v166, v167
	v_mul_f32_e32 v170, 0x3e0293ee, v70
	v_mul_f32_e32 v171, 0x3e0293ee, v71
	v_max3_f32 v162, v162, v168, v169
	v_mul_f32_e32 v172, 0x3e0293ee, v72
	v_mul_f32_e32 v173, 0x3e0293ee, v73
	v_max3_f32 v162, v162, v170, v171
	v_mul_f32_e32 v174, 0x3e0293ee, v74
	v_mul_f32_e32 v175, 0x3e0293ee, v75
	v_max3_f32 v162, v162, v172, v173
	v_mul_f32_e32 v176, 0x3e0293ee, v76
	v_mul_f32_e32 v177, 0x3e0293ee, v77
	v_max3_f32 v162, v162, v174, v175
	v_mul_f32_e32 v178, 0x3e0293ee, v78
	v_mul_f32_e32 v179, 0x3e0293ee, v79
	v_max3_f32 v162, v162, v176, v177
	v_max3_f32 v162, v162, v178, v179
	v_mov_b32_e32 v164, v162
	s_nop 1
	v_permlane32_swap_b32_e32 v162, v164
	v_max3_f32 v162, v163, v162, v164
	v_fma_f32 v64, v64, s94, -v162
	v_sub_f32_e32 v164, v163, v162
	v_exp_f32_e32 v163, v64
	v_fma_f32 v64, v65, s94, -v162
	v_exp_f32_e32 v65, v64
	v_fma_f32 v64, v66, s94, -v162
	v_exp_f32_e32 v66, v64
	v_fma_f32 v64, v67, s94, -v162
	v_exp_f32_e32 v67, v64
	v_fma_f32 v64, v68, s94, -v162
	v_exp_f32_e32 v68, v64
	v_fma_f32 v64, v69, s94, -v162
	v_exp_f32_e32 v69, v64
	v_fma_f32 v64, v70, s94, -v162
	v_exp_f32_e32 v70, v64
	v_fma_f32 v64, v71, s94, -v162
	v_exp_f32_e32 v71, v64
	v_fma_f32 v64, v72, s94, -v162
	ds_read_b128 v[176:179], v202 offset:17408
	ds_read_b128 v[180:183], v202 offset:17440
	ds_read_b128 v[184:187], v202 offset:22016
	ds_read_b128 v[188:191], v202 offset:22048
	ds_read_b128 v[192:195], v202 offset:26624
	ds_read_b128 v[196:199], v202 offset:26656
	ds_read_b128 v[204:207], v202 offset:31232
	ds_read_b128 v[208:211], v202 offset:31264
	v_exp_f32_e32 v72, v64
	v_fma_f32 v64, v73, s94, -v162
	v_exp_f32_e32 v73, v64
	v_fma_f32 v64, v74, s94, -v162
	v_exp_f32_e32 v74, v64
	v_fma_f32 v64, v75, s94, -v162
	v_exp_f32_e32 v75, v64
	v_fma_f32 v64, v76, s94, -v162
	v_exp_f32_e32 v76, v64
	v_fma_f32 v64, v77, s94, -v162
	v_fma_f32 v80, v80, s94, -v162
	v_fma_f32 v81, v81, s94, -v162
	v_fma_f32 v82, v82, s94, -v162
	v_fma_f32 v83, v83, s94, -v162
	v_fma_f32 v84, v84, s94, -v162
	v_fma_f32 v85, v85, s94, -v162
; #define LAS __attribute__((address_space(3)))
; __device__ __forceinline__ float ex2(float x) { return __builtin_amdgcn_exp2f(x); }
; #define MFMA32(a, b, c) __builtin_amdgcn_mfma_f32_32x32x16_bf16((a), (b), (c), 0, 0, 0)
;     ...
;             for (int i = 0; i < 32; ++i) { x[i] = ex2(x[i] - mn); rs += x[i]; }
;             l = l * alpha + rs;
; #pragma unroll
;             for (int db = 0; db < 4; ++db)
; #pragma unroll
;                 for (int i = 0; i < 16; ++i) o[db][i] *= alpha;
;             bf16x8 pf[4];
; #pragma unroll
;             for (int j = 0; j < 4; ++j) pf[j] = pack8(x[8 * j], x[8 * j + 1], x[8 * j + 2], x[8 * j + 3], x[8 * j + 4], x[8 * j + 5], x[8 * j + 6], x[8 * j + 7]);
; #pragma unroll
;             for (int jh = 0; jh < 2; ++jh) {
;                 bf16x8 va[2][4];
; #pragma unroll
;                 for (int j = 0; j < 2; ++j)
; #pragma unroll
;                     for (int db = 0; db < 4; ++db) va[j][db] = *(const LAS bf16x8*)(base + voff + db * 32 * AT_VROW + (2 * jh + j) * 32);
;                 __builtin_amdgcn_sched_barrier(0);
; #pragma unroll
;                 for (int j = 0; j < 2; ++j)
; #pragma unroll
;                     for (int db = 0; db < 4; ++db) o[db] = MFMA32(va[j][db], pf[2 * jh + j], o[db]);
;                 __builtin_amdgcn_sched_barrier(0);
;             }
;             if (MODE == 0 && kt > kt0 && k0 <= tq0) {
;                 const float ub = qn + cbl[0];
;                 wdone = __all(ub < m - 30.f);
;             }
;         }
;         if (kt > kt0) AT_WRITE(cur ^ 1);
	v_fma_f32 v86, v86, s94, -v162
	v_fma_f32 v87, v87, s94, -v162
	v_fma_f32 v88, v88, s94, -v162
	v_fma_f32 v89, v89, s94, -v162
	v_fma_f32 v90, v90, s94, -v162
	v_fma_f32 v91, v91, s94, -v162
	v_fma_f32 v92, v92, s94, -v162
	v_fma_f32 v93, v93, s94, -v162
	v_fma_f32 v94, v94, s94, -v162
	v_fma_f32 v95, v95, s94, -v162
	v_exp_f32_e32 v77, v64
	v_fma_f32 v78, v78, s94, -v162
	v_exp_f32_e32 v64, v164
	v_fma_f32 v79, v79, s94, -v162
	v_exp_f32_e32 v80, v80
	v_exp_f32_e32 v81, v81
	v_exp_f32_e32 v82, v82
	v_exp_f32_e32 v83, v83
	v_exp_f32_e32 v84, v84
	v_exp_f32_e32 v85, v85
	v_exp_f32_e32 v86, v86
	v_exp_f32_e32 v87, v87
	v_exp_f32_e32 v88, v88
	v_exp_f32_e32 v89, v89
	v_exp_f32_e32 v90, v90
	v_exp_f32_e32 v91, v91
	v_exp_f32_e32 v92, v92
	v_exp_f32_e32 v93, v93
	v_exp_f32_e32 v94, v94
	v_exp_f32_e32 v95, v95
	v_exp_f32_e32 v78, v78
	v_exp_f32_e32 v79, v79
	v_mul_f32_e32 v62, v62, v64
	v_mul_f32_e32 v63, v63, v64
	v_mul_f32_e32 v60, v60, v64
	v_mul_f32_e32 v61, v61, v64
	v_mul_f32_e32 v58, v58, v64
	v_mul_f32_e32 v59, v59, v64
	v_mul_f32_e32 v56, v56, v64
	v_mul_f32_e32 v57, v57, v64
	v_mul_f32_e32 v54, v54, v64
	v_mul_f32_e32 v55, v55, v64
	v_mul_f32_e32 v52, v52, v64
	v_mul_f32_e32 v53, v53, v64
	v_mul_f32_e32 v50, v50, v64
	v_mul_f32_e32 v51, v51, v64
	v_mul_f32_e32 v48, v48, v64
	v_mul_f32_e32 v49, v49, v64
	v_mul_f32_e32 v46, v46, v64
	v_mul_f32_e32 v47, v47, v64
	v_mul_f32_e32 v44, v44, v64
	v_mul_f32_e32 v45, v45, v64
	v_mul_f32_e32 v42, v42, v64
	v_mul_f32_e32 v43, v43, v64
	v_mul_f32_e32 v40, v40, v64
	v_mul_f32_e32 v41, v41, v64
	v_mul_f32_e32 v38, v38, v64
	v_mul_f32_e32 v39, v39, v64
	v_mul_f32_e32 v36, v36, v64
	v_mul_f32_e32 v37, v37, v64
	v_mul_f32_e32 v34, v34, v64
	v_mul_f32_e32 v35, v35, v64
	v_mul_f32_e32 v32, v32, v64
	v_mul_f32_e32 v33, v33, v64
	v_mul_f32_e32 v30, v30, v64
	v_mul_f32_e32 v31, v31, v64
	v_mul_f32_e32 v28, v28, v64
	v_mul_f32_e32 v29, v29, v64
	v_mul_f32_e32 v26, v26, v64
	v_mul_f32_e32 v27, v27, v64
	v_mul_f32_e32 v24, v24, v64
	v_mul_f32_e32 v25, v25, v64
	v_mul_f32_e32 v22, v22, v64
	v_mul_f32_e32 v23, v23, v64
	v_mul_f32_e32 v20, v20, v64
	v_mul_f32_e32 v21, v21, v64
	v_mul_f32_e32 v18, v18, v64
	v_mul_f32_e32 v19, v19, v64
	v_mul_f32_e32 v16, v16, v64
	v_mul_f32_e32 v17, v17, v64
	v_mul_f32_e32 v14, v14, v64
	v_mul_f32_e32 v15, v15, v64
	v_mul_f32_e32 v12, v12, v64
	v_mul_f32_e32 v13, v13, v64
	v_mul_f32_e32 v10, v10, v64
	v_mul_f32_e32 v11, v11, v64
	v_mul_f32_e32 v8, v8, v64
	v_mul_f32_e32 v9, v9, v64
	v_mul_f32_e32 v6, v6, v64
	v_mul_f32_e32 v7, v7, v64
	v_mul_f32_e32 v4, v4, v64
	v_mul_f32_e32 v5, v5, v64
	v_mul_f32_e32 v2, v2, v64
	v_mul_f32_e32 v3, v3, v64
	v_mul_f32_e32 v0, v0, v64
	v_mul_f32_e32 v1, v1, v64
	v_cvt_pk_bf16_f32 v164, v80, v81
	v_cvt_pk_bf16_f32 v165, v82, v83
	v_cvt_pk_bf16_f32 v166, v84, v85
	v_cvt_pk_bf16_f32 v167, v86, v87
	v_cvt_pk_bf16_f32 v168, v88, v89
	v_cvt_pk_bf16_f32 v169, v90, v91
	v_cvt_pk_bf16_f32 v170, v92, v93
	v_cvt_pk_bf16_f32 v171, v94, v95
	v_cvt_pk_bf16_f32 v172, v163, v65
	v_cvt_pk_bf16_f32 v173, v66, v67
	v_cvt_pk_bf16_f32 v174, v68, v69
	v_cvt_pk_bf16_f32 v175, v70, v71
	v_cvt_pk_bf16_f32 v212, v72, v73
	v_cvt_pk_bf16_f32 v213, v74, v75
	v_cvt_pk_bf16_f32 v214, v76, v77
	v_cvt_pk_bf16_f32 v215, v78, v79
	s_waitcnt lgkmcnt(0)
	v_mfma_f32_32x32x16_bf16 v[48:63], v[176:179], v[164:167], v[48:63]
	v_mfma_f32_32x32x16_bf16 v[32:47], v[184:187], v[164:167], v[32:47]
	v_mfma_f32_32x32x16_bf16 v[16:31], v[192:195], v[164:167], v[16:31]
	v_mfma_f32_32x32x16_bf16 v[0:15], v[204:207], v[164:167], v[0:15]
	v_mfma_f32_32x32x16_bf16 v[48:63], v[180:183], v[168:171], v[48:63]
	v_mfma_f32_32x32x16_bf16 v[32:47], v[188:191], v[168:171], v[32:47]
	v_mfma_f32_32x32x16_bf16 v[16:31], v[196:199], v[168:171], v[16:31]
	v_mfma_f32_32x32x16_bf16 v[0:15], v[208:211], v[168:171], v[0:15]
	ds_read_b128 v[164:167], v202 offset:17472
	ds_read_b128 v[168:171], v202 offset:17504
	ds_read_b128 v[176:179], v202 offset:22080
	ds_read_b128 v[180:183], v202 offset:22112
	ds_read_b128 v[184:187], v202 offset:26688
	ds_read_b128 v[188:191], v202 offset:26720
	ds_read_b128 v[192:195], v202 offset:31296
	ds_read_b128 v[196:199], v202 offset:31328
	s_waitcnt lgkmcnt(0)
	v_mfma_f32_32x32x16_bf16 v[48:63], v[164:167], v[172:175], v[48:63]
	v_mfma_f32_32x32x16_bf16 v[32:47], v[176:179], v[172:175], v[32:47]
	v_mfma_f32_32x32x16_bf16 v[16:31], v[184:187], v[172:175], v[16:31]
	v_mfma_f32_32x32x16_bf16 v[0:15], v[192:195], v[172:175], v[0:15]
	v_mfma_f32_32x32x16_bf16 v[48:63], v[168:171], v[212:215], v[48:63]
	v_mfma_f32_32x32x16_bf16 v[32:47], v[180:183], v[212:215], v[32:47]
	v_mfma_f32_32x32x16_bf16 v[16:31], v[188:191], v[212:215], v[16:31]
	v_mfma_f32_32x32x16_bf16 v[0:15], v[196:199], v[212:215], v[0:15]
	s_andn2_b64 vcc, exec, s[4:5]
	s_cbranch_vccnz .LBB0_776
	s_mul_i32 s8, s8, 0x8d00
	s_add_i32 s4, s8, 0
	v_add3_u32 v164, s4, v151, v148
	v_add3_u32 v165, s4, v160, v150
	v_add3_u32 v166, s4, v161, v150
	s_waitcnt vmcnt(0)
	ds_write_b128 v164, v[128:131]
	ds_write_b128 v164, v[132:135] offset:8704
	ds_write_b128 v165, v[136:139] offset:17408
	ds_write_b128 v166, v[140:143] offset:17408
